# branch-GEMM epilogue: 16 gate-row loads fetched together; xcd barrier after phase 0; plus v19 changes
# speedup vs baseline: 1.0172x; 1.0104x over previous
; __device__ __forceinline__ unsigned pk2(float lo, float hi) { const f32x2_t v = {lo, hi}; const bf16x2_t b = __builtin_convertvector(v, bf16x2_t); return __builtin_bit_cast(unsigned, b); }
; __device__ __forceinline__ float lo16(unsigned w) { return __uint_as_float(w << 16); }
; __device__ __forceinline__ float hi16(unsigned w) { return __uint_as_float(w & 0xffff0000u); }
;     __device__ __forceinline__ void operator()(const f32x4 (&acc)[2][2][4][2], const Unit& u, int wr, int wc, int fr, int fq) const {
;     ...
;                 const int rl = rloc + ai * HALF + m * 16;
;                 const unsigned char* gp_ = (const unsigned char*)(Gp + (size_t)(u.pm * BM + rl) * ldg) + colg;
; #pragma unroll
;                 for (int bj = 0; bj < 2; ++bj) {
;                     const u32x2 gp = *(const u32x2*)(gp_ + bj * HALF);
;                     const f32x4 v0 = acc[ai][bj][m][0] * (1.0f / 255.0f), v1 = acc[ai][bj][m][1] * (1.0f / 255.0f);
;                     f32x4 z0 = {(float)(gp.x & 255u) * v0[0], (float)((gp.x >> 8) & 255u) * v0[1], (float)((gp.x >> 16) & 255u) * v0[2], (float)(gp.x >> 24) * v0[3]};
;                     f32x4 z1 = {(float)(gp.y & 255u) * v1[0], (float)((gp.y >> 8) & 255u) * v1[1], (float)((gp.y >> 16) & 255u) * v1[2], (float)(gp.y >> 24) * v1[3]};
;                     if (ctx) {
;                         float* pp = part + ((size_t)(b * 256 + rl)) * D + colm + bj * HALF;
;                         *(f32x4*)pp = z0; *(f32x4*)(pp + 4) = z1;
;                     } else {
;                         bf16_t* mp = MG + (size_t)(u.pm * BM + rl) * D + colm + bj * HALF;
;                         if (b != 0) { const u32x4 pv = *(const u32x4*)mp;
;                             z0 += (f32x4){lo16(pv.x), hi16(pv.x), lo16(pv.y), hi16(pv.y)}; z1 += (f32x4){lo16(pv.z), hi16(pv.z), lo16(pv.w), hi16(pv.w)}; }
;                         u32x4 w; w.x = pk2(z0[0], z0[1]); w.y = pk2(z0[2], z0[3]); w.z = pk2(z1[0], z1[1]); w.w = pk2(z1[2], z1[3]);
;                         *(u32x4*)mp = w;
.LBB0_190:
	s_lshl_b32 s4, s2, 8
	v_or_b32_e32 v146, s4, v167
	s_and_b32 s4, s4, 0x300
	s_cmp_lg_u32 s20, 64
	s_cselect_b64 s[58:59], -1, 0
	s_lshl_b32 s7, s20, 8
	v_add_u32_e32 v130, s7, v154
	v_mov_b64_e32 v[132:133], s[90:91]
	v_ashrrev_i32_e32 v147, 31, v146
	v_mad_i64_i32 v[132:133], s[22:23], v130, s21, v[132:133]
	v_lshl_add_u64 v[150:151], v[132:133], 0, v[146:147]
	v_add_u32_e32 v180, s7, v154
	v_mov_b64_e32 v[182:183], s[90:91]
	v_mad_i64_i32 v[182:183], s[22:23], v180, s21, v[182:183]
	v_lshl_add_u64 v[182:183], v[182:183], 0, v[146:147]
	global_load_dwordx2 v[218:219], v[182:183], off
	global_load_dwordx2 v[220:221], v[182:183], off offset:128
	v_add_u32_e32 v180, s7, v168
	v_mov_b64_e32 v[182:183], s[90:91]
	v_mad_i64_i32 v[182:183], s[22:23], v180, s21, v[182:183]
	v_lshl_add_u64 v[182:183], v[182:183], 0, v[146:147]
	global_load_dwordx2 v[222:223], v[182:183], off
	global_load_dwordx2 v[224:225], v[182:183], off offset:128
	v_add_u32_e32 v180, s7, v169
	v_mov_b64_e32 v[182:183], s[90:91]
	v_mad_i64_i32 v[182:183], s[22:23], v180, s21, v[182:183]
	v_lshl_add_u64 v[182:183], v[182:183], 0, v[146:147]
	global_load_dwordx2 v[226:227], v[182:183], off
	global_load_dwordx2 v[228:229], v[182:183], off offset:128
	v_add_u32_e32 v180, s7, v170
	v_mov_b64_e32 v[182:183], s[90:91]
	v_mad_i64_i32 v[182:183], s[22:23], v180, s21, v[182:183]
	v_lshl_add_u64 v[182:183], v[182:183], 0, v[146:147]
	global_load_dwordx2 v[230:231], v[182:183], off
	global_load_dwordx2 v[232:233], v[182:183], off offset:128
	v_add_u32_e32 v180, s7, v171
	v_mov_b64_e32 v[182:183], s[90:91]
	v_mad_i64_i32 v[182:183], s[22:23], v180, s21, v[182:183]
	v_lshl_add_u64 v[182:183], v[182:183], 0, v[146:147]
	global_load_dwordx2 v[234:235], v[182:183], off
	global_load_dwordx2 v[236:237], v[182:183], off offset:128
	v_add_u32_e32 v180, s7, v172
	v_mov_b64_e32 v[182:183], s[90:91]
	v_mad_i64_i32 v[182:183], s[22:23], v180, s21, v[182:183]
	v_lshl_add_u64 v[182:183], v[182:183], 0, v[146:147]
	global_load_dwordx2 v[238:239], v[182:183], off
	global_load_dwordx2 v[240:241], v[182:183], off offset:128
	v_add_u32_e32 v180, s7, v173
	v_mov_b64_e32 v[182:183], s[90:91]
	v_mad_i64_i32 v[182:183], s[22:23], v180, s21, v[182:183]
	v_lshl_add_u64 v[182:183], v[182:183], 0, v[146:147]
	global_load_dwordx2 v[194:195], v[182:183], off
	global_load_dwordx2 v[196:197], v[182:183], off offset:128
	v_add_u32_e32 v180, s7, v174
	v_mov_b64_e32 v[182:183], s[90:91]
	v_mad_i64_i32 v[182:183], s[22:23], v180, s21, v[182:183]
	v_lshl_add_u64 v[182:183], v[182:183], 0, v[146:147]
	global_load_dwordx2 v[198:199], v[182:183], off
	global_load_dwordx2 v[200:201], v[182:183], off offset:128
	s_cmp_gt_u32 s2, 3
	v_ashrrev_i32_e32 v131, 31, v130
	v_or_b32_e32 v176, s4, v167
	s_cselect_b64 s[4:5], -1, 0
	v_lshlrev_b64 v[130:131], 11, v[130:131]
	v_pk_mul_f32 v[128:129], v[128:129], s[96:97] op_sel_hi:[1,0]
	v_pk_mul_f32 v[126:127], v[126:127], s[96:97] op_sel_hi:[1,0]
	v_pk_mul_f32 v[134:135], v[124:125], s[96:97] op_sel_hi:[1,0]
	v_pk_mul_f32 v[136:137], v[122:123], s[96:97] op_sel_hi:[1,0]
	v_lshl_add_u64 v[148:149], s[84:85], 0, v[130:131]
	v_cndmask_b32_e64 v130, 0, 1, s[4:5]
	s_mov_b64 s[46:47], -1
	s_and_b64 vcc, exec, s[58:59]
	v_lshlrev_b32_e32 v0, 1, v176
	v_cmp_ne_u32_e64 s[4:5], 1, v130
	s_waitcnt vmcnt(0)
	v_cvt_f32_ubyte1_e32 v123, v218
	v_cvt_f32_ubyte0_e32 v122, v218
	v_cvt_f32_ubyte3_e32 v125, v218
	v_cvt_f32_ubyte2_e32 v124, v218
	v_pk_mul_f32 v[124:125], v[128:129], v[124:125]
	v_pk_mul_f32 v[122:123], v[126:127], v[122:123]
	v_cvt_f32_ubyte1_e32 v127, v219
	v_cvt_f32_ubyte0_e32 v126, v219
	v_cvt_f32_ubyte3_e32 v129, v219
	v_cvt_f32_ubyte2_e32 v128, v219
	v_pk_mul_f32 v[128:129], v[134:135], v[128:129]
	v_pk_mul_f32 v[126:127], v[136:137], v[126:127]
	s_cbranch_vccz .LBB0_194
	v_mov_b64_e32 v[136:137], v[128:129]
	v_mov_b64_e32 v[132:133], v[124:125]
	v_lshl_add_u64 v[152:153], v[148:149], 0, v[0:1]
	s_and_b64 vcc, exec, s[4:5]
	v_mov_b64_e32 v[134:135], v[126:127]
	v_mov_b64_e32 v[130:131], v[122:123]
	s_cbranch_vccnz .LBB0_193
	global_load_dwordx4 v[130:133], v[152:153], off
	s_waitcnt vmcnt(0)
	v_lshlrev_b32_e32 v134, 16, v130
	v_and_b32_e32 v135, 0xffff0000, v130
	v_lshlrev_b32_e32 v130, 16, v131
	v_and_b32_e32 v131, 0xffff0000, v131
	v_lshlrev_b32_e32 v178, 16, v132
	v_and_b32_e32 v179, 0xffff0000, v132
	v_lshlrev_b32_e32 v136, 16, v133
	v_and_b32_e32 v137, 0xffff0000, v133
	v_pk_add_f32 v[132:133], v[124:125], v[130:131]
	v_pk_add_f32 v[130:131], v[122:123], v[134:135]
	v_pk_add_f32 v[136:137], v[128:129], v[136:137]
	v_pk_add_f32 v[134:135], v[126:127], v[178:179]

; __device__ __forceinline__ unsigned pk2(float lo, float hi) { const f32x2_t v = {lo, hi}; const bf16x2_t b = __builtin_convertvector(v, bf16x2_t); return __builtin_bit_cast(unsigned, b); }
; __device__ __forceinline__ float lo16(unsigned w) { return __uint_as_float(w << 16); }
; __device__ __forceinline__ float hi16(unsigned w) { return __uint_as_float(w & 0xffff0000u); }
;     __device__ __forceinline__ void operator()(const f32x4 (&acc)[2][2][4][2], const Unit& u, int wr, int wc, int fr, int fq) const {
;     ...
;                     const u32x2 gp = *(const u32x2*)(gp_ + bj * HALF);
;                     const f32x4 v0 = acc[ai][bj][m][0] * (1.0f / 255.0f), v1 = acc[ai][bj][m][1] * (1.0f / 255.0f);
;                     f32x4 z0 = {(float)(gp.x & 255u) * v0[0], (float)((gp.x >> 8) & 255u) * v0[1], (float)((gp.x >> 16) & 255u) * v0[2], (float)(gp.x >> 24) * v0[3]};
;                     f32x4 z1 = {(float)(gp.y & 255u) * v1[0], (float)((gp.y >> 8) & 255u) * v1[1], (float)((gp.y >> 16) & 255u) * v1[2], (float)(gp.y >> 24) * v1[3]};
;                     if (ctx) {
;                         float* pp = part + ((size_t)(b * 256 + rl)) * D + colm + bj * HALF;
;                         *(f32x4*)pp = z0; *(f32x4*)(pp + 4) = z1;
;                     } else {
;                         bf16_t* mp = MG + (size_t)(u.pm * BM + rl) * D + colm + bj * HALF;
;                         if (b != 0) { const u32x4 pv = *(const u32x4*)mp;
;                             z0 += (f32x4){lo16(pv.x), hi16(pv.x), lo16(pv.y), hi16(pv.y)}; z1 += (f32x4){lo16(pv.z), hi16(pv.z), lo16(pv.w), hi16(pv.w)}; }
;                         u32x4 w; w.x = pk2(z0[0], z0[1]); w.y = pk2(z0[2], z0[3]); w.z = pk2(z1[0], z1[1]); w.w = pk2(z1[2], z1[3]);
;                         *(u32x4*)mp = w;
.LBB0_196:
	s_nop 0
	v_pk_mul_f32 v[120:121], v[120:121], s[96:97] op_sel_hi:[1,0]
	v_pk_mul_f32 v[118:119], v[118:119], s[96:97] op_sel_hi:[1,0]
	v_pk_mul_f32 v[124:125], v[116:117], s[96:97] op_sel_hi:[1,0]
	v_pk_mul_f32 v[126:127], v[114:115], s[96:97] op_sel_hi:[1,0]
	v_readlane_b32 s66, v253, 19
	s_andn2_b64 vcc, exec, s[58:59]
	v_readlane_b32 s67, v253, 20
	s_nop 0
	v_cvt_f32_ubyte1_e32 v115, v220
	v_cvt_f32_ubyte0_e32 v114, v220
	v_cvt_f32_ubyte3_e32 v117, v220
	v_cvt_f32_ubyte2_e32 v116, v220
	v_pk_mul_f32 v[116:117], v[120:121], v[116:117]
	v_pk_mul_f32 v[114:115], v[118:119], v[114:115]
	v_cvt_f32_ubyte1_e32 v119, v221
	v_cvt_f32_ubyte0_e32 v118, v221
	v_cvt_f32_ubyte3_e32 v121, v221
	v_cvt_f32_ubyte2_e32 v120, v221
	v_cndmask_b32_e64 v122, 0, 1, s[58:59]
	v_pk_mul_f32 v[120:121], v[124:125], v[120:121]
	v_pk_mul_f32 v[118:119], v[126:127], v[118:119]
	v_cmp_ne_u32_e64 s[46:47], 1, v122
	s_cbranch_vccnz .LBB0_200
	v_mov_b64_e32 v[128:129], v[120:121]
	v_mov_b64_e32 v[124:125], v[116:117]
	v_lshl_add_u64 v[134:135], v[148:149], 0, v[0:1]
	s_and_b64 vcc, exec, s[4:5]
	v_mov_b64_e32 v[126:127], v[118:119]
	v_mov_b64_e32 v[122:123], v[114:115]
	s_cbranch_vccnz .LBB0_199
	global_load_dwordx4 v[122:125], v[134:135], off offset:256
	s_waitcnt vmcnt(0)
	v_lshlrev_b32_e32 v126, 16, v122
	v_and_b32_e32 v127, 0xffff0000, v122
	v_lshlrev_b32_e32 v122, 16, v123
	v_and_b32_e32 v123, 0xffff0000, v123
	v_lshlrev_b32_e32 v136, 16, v124
	v_and_b32_e32 v137, 0xffff0000, v124
	v_lshlrev_b32_e32 v128, 16, v125
	v_and_b32_e32 v129, 0xffff0000, v125
	v_pk_add_f32 v[124:125], v[116:117], v[122:123]
	v_pk_add_f32 v[122:123], v[114:115], v[126:127]
	v_pk_add_f32 v[128:129], v[120:121], v[128:129]
	v_pk_add_f32 v[126:127], v[118:119], v[136:137]

; __device__ __forceinline__ unsigned pk2(float lo, float hi) { const f32x2_t v = {lo, hi}; const bf16x2_t b = __builtin_convertvector(v, bf16x2_t); return __builtin_bit_cast(unsigned, b); }
; __device__ __forceinline__ float lo16(unsigned w) { return __uint_as_float(w << 16); }
; __device__ __forceinline__ float hi16(unsigned w) { return __uint_as_float(w & 0xffff0000u); }
;     __device__ __forceinline__ void operator()(const f32x4 (&acc)[2][2][4][2], const Unit& u, int wr, int wc, int fr, int fq) const {
;     ...
;                 const int rl = rloc + ai * HALF + m * 16;
;                 const unsigned char* gp_ = (const unsigned char*)(Gp + (size_t)(u.pm * BM + rl) * ldg) + colg;
; #pragma unroll
;                 for (int bj = 0; bj < 2; ++bj) {
;                     const u32x2 gp = *(const u32x2*)(gp_ + bj * HALF);
;                     const f32x4 v0 = acc[ai][bj][m][0] * (1.0f / 255.0f), v1 = acc[ai][bj][m][1] * (1.0f / 255.0f);
;                     f32x4 z0 = {(float)(gp.x & 255u) * v0[0], (float)((gp.x >> 8) & 255u) * v0[1], (float)((gp.x >> 16) & 255u) * v0[2], (float)(gp.x >> 24) * v0[3]};
;                     f32x4 z1 = {(float)(gp.y & 255u) * v1[0], (float)((gp.y >> 8) & 255u) * v1[1], (float)((gp.y >> 16) & 255u) * v1[2], (float)(gp.y >> 24) * v1[3]};
;                     if (ctx) {
;                         float* pp = part + ((size_t)(b * 256 + rl)) * D + colm + bj * HALF;
;                         *(f32x4*)pp = z0; *(f32x4*)(pp + 4) = z1;
;                     } else {
;                         bf16_t* mp = MG + (size_t)(u.pm * BM + rl) * D + colm + bj * HALF;
;                         if (b != 0) { const u32x4 pv = *(const u32x4*)mp;
;                             z0 += (f32x4){lo16(pv.x), hi16(pv.x), lo16(pv.y), hi16(pv.y)}; z1 += (f32x4){lo16(pv.z), hi16(pv.z), lo16(pv.w), hi16(pv.w)}; }
;                         u32x4 w; w.x = pk2(z0[0], z0[1]); w.y = pk2(z0[2], z0[3]); w.z = pk2(z1[0], z1[1]); w.w = pk2(z1[2], z1[3]);
;                         *(u32x4*)mp = w;
.LBB0_202:
	s_nop 0
	v_add_u32_e32 v114, s7, v168
	v_mov_b64_e32 v[116:117], s[90:91]
	v_mad_i64_i32 v[116:117], s[22:23], v114, s21, v[116:117]
	v_lshl_add_u64 v[122:123], v[116:117], 0, v[146:147]
	s_nop 0
	v_ashrrev_i32_e32 v115, 31, v114
	v_pk_mul_f32 v[112:113], v[112:113], s[96:97] op_sel_hi:[1,0]
	v_pk_mul_f32 v[110:111], v[110:111], s[96:97] op_sel_hi:[1,0]
	v_pk_mul_f32 v[118:119], v[108:109], s[96:97] op_sel_hi:[1,0]
	v_pk_mul_f32 v[120:121], v[106:107], s[96:97] op_sel_hi:[1,0]
	v_lshlrev_b64 v[114:115], 11, v[114:115]
	s_mov_b64 s[58:59], -1
	s_and_b64 vcc, exec, s[46:47]
	v_lshl_add_u64 v[124:125], s[84:85], 0, v[114:115]
	s_nop 0
	v_cvt_f32_ubyte1_e32 v107, v222
	v_cvt_f32_ubyte0_e32 v106, v222
	v_cvt_f32_ubyte3_e32 v109, v222
	v_cvt_f32_ubyte2_e32 v108, v222
	v_pk_mul_f32 v[108:109], v[112:113], v[108:109]
	v_pk_mul_f32 v[106:107], v[110:111], v[106:107]
	v_cvt_f32_ubyte1_e32 v111, v223
	v_cvt_f32_ubyte0_e32 v110, v223
	v_cvt_f32_ubyte3_e32 v113, v223
	v_cvt_f32_ubyte2_e32 v112, v223
	v_pk_mul_f32 v[112:113], v[118:119], v[112:113]
	v_pk_mul_f32 v[110:111], v[120:121], v[110:111]
	s_cbranch_vccnz .LBB0_206
	v_mov_b64_e32 v[120:121], v[112:113]
	v_mov_b64_e32 v[116:117], v[108:109]
	v_lshl_add_u64 v[126:127], v[124:125], 0, v[0:1]
	s_and_b64 vcc, exec, s[4:5]
	v_mov_b64_e32 v[118:119], v[110:111]
	v_mov_b64_e32 v[114:115], v[106:107]
	s_cbranch_vccnz .LBB0_205
	global_load_dwordx4 v[114:117], v[126:127], off
	s_waitcnt vmcnt(0)
	v_lshlrev_b32_e32 v118, 16, v114
	v_and_b32_e32 v119, 0xffff0000, v114
	v_lshlrev_b32_e32 v114, 16, v115
	v_and_b32_e32 v115, 0xffff0000, v115
	v_lshlrev_b32_e32 v128, 16, v116
	v_and_b32_e32 v129, 0xffff0000, v116
	v_lshlrev_b32_e32 v120, 16, v117
	v_and_b32_e32 v121, 0xffff0000, v117
	v_pk_add_f32 v[116:117], v[108:109], v[114:115]
	v_pk_add_f32 v[114:115], v[106:107], v[118:119]
	v_pk_add_f32 v[120:121], v[112:113], v[120:121]
	v_pk_add_f32 v[118:119], v[110:111], v[128:129]

; __device__ __forceinline__ unsigned pk2(float lo, float hi) { const f32x2_t v = {lo, hi}; const bf16x2_t b = __builtin_convertvector(v, bf16x2_t); return __builtin_bit_cast(unsigned, b); }
; __device__ __forceinline__ float lo16(unsigned w) { return __uint_as_float(w << 16); }
; __device__ __forceinline__ float hi16(unsigned w) { return __uint_as_float(w & 0xffff0000u); }
;     __device__ __forceinline__ void operator()(const f32x4 (&acc)[2][2][4][2], const Unit& u, int wr, int wc, int fr, int fq) const {
;     ...
;                     const u32x2 gp = *(const u32x2*)(gp_ + bj * HALF);
;                     const f32x4 v0 = acc[ai][bj][m][0] * (1.0f / 255.0f), v1 = acc[ai][bj][m][1] * (1.0f / 255.0f);
;                     f32x4 z0 = {(float)(gp.x & 255u) * v0[0], (float)((gp.x >> 8) & 255u) * v0[1], (float)((gp.x >> 16) & 255u) * v0[2], (float)(gp.x >> 24) * v0[3]};
;                     f32x4 z1 = {(float)(gp.y & 255u) * v1[0], (float)((gp.y >> 8) & 255u) * v1[1], (float)((gp.y >> 16) & 255u) * v1[2], (float)(gp.y >> 24) * v1[3]};
;                     if (ctx) {
;                         float* pp = part + ((size_t)(b * 256 + rl)) * D + colm + bj * HALF;
;                         *(f32x4*)pp = z0; *(f32x4*)(pp + 4) = z1;
;                     } else {
;                         bf16_t* mp = MG + (size_t)(u.pm * BM + rl) * D + colm + bj * HALF;
;                         if (b != 0) { const u32x4 pv = *(const u32x4*)mp;
;                             z0 += (f32x4){lo16(pv.x), hi16(pv.x), lo16(pv.y), hi16(pv.y)}; z1 += (f32x4){lo16(pv.z), hi16(pv.z), lo16(pv.w), hi16(pv.w)}; }
;                         u32x4 w; w.x = pk2(z0[0], z0[1]); w.y = pk2(z0[2], z0[3]); w.z = pk2(z1[0], z1[1]); w.w = pk2(z1[2], z1[3]);
;                         *(u32x4*)mp = w;
.LBB0_208:
	s_nop 0
	v_pk_mul_f32 v[104:105], v[104:105], s[96:97] op_sel_hi:[1,0]
	v_pk_mul_f32 v[102:103], v[102:103], s[96:97] op_sel_hi:[1,0]
	v_pk_mul_f32 v[108:109], v[100:101], s[96:97] op_sel_hi:[1,0]
	v_pk_mul_f32 v[110:111], v[98:99], s[96:97] op_sel_hi:[1,0]
	s_mov_b64 s[58:59], -1
	s_and_b64 vcc, exec, s[46:47]
	s_nop 0
	v_cvt_f32_ubyte1_e32 v99, v224
	v_cvt_f32_ubyte0_e32 v98, v224
	v_cvt_f32_ubyte3_e32 v101, v224
	v_cvt_f32_ubyte2_e32 v100, v224
	v_pk_mul_f32 v[100:101], v[104:105], v[100:101]
	v_pk_mul_f32 v[98:99], v[102:103], v[98:99]
	v_cvt_f32_ubyte1_e32 v103, v225
	v_cvt_f32_ubyte0_e32 v102, v225
	v_cvt_f32_ubyte3_e32 v105, v225
	v_cvt_f32_ubyte2_e32 v104, v225
	v_pk_mul_f32 v[104:105], v[108:109], v[104:105]
	v_pk_mul_f32 v[102:103], v[110:111], v[102:103]
	s_cbranch_vccnz .LBB0_212
	v_mov_b64_e32 v[112:113], v[104:105]
	v_mov_b64_e32 v[108:109], v[100:101]
	v_lshl_add_u64 v[116:117], v[124:125], 0, v[0:1]
	s_and_b64 vcc, exec, s[4:5]
	v_mov_b64_e32 v[110:111], v[102:103]
	v_mov_b64_e32 v[106:107], v[98:99]
	s_cbranch_vccnz .LBB0_211
	global_load_dwordx4 v[106:109], v[116:117], off offset:256
	s_waitcnt vmcnt(0)
	v_lshlrev_b32_e32 v110, 16, v106
	v_and_b32_e32 v111, 0xffff0000, v106
	v_lshlrev_b32_e32 v106, 16, v107
	v_and_b32_e32 v107, 0xffff0000, v107
	v_lshlrev_b32_e32 v118, 16, v108
	v_and_b32_e32 v119, 0xffff0000, v108
	v_lshlrev_b32_e32 v112, 16, v109
	v_and_b32_e32 v113, 0xffff0000, v109
	v_pk_add_f32 v[108:109], v[100:101], v[106:107]
	v_pk_add_f32 v[106:107], v[98:99], v[110:111]
	v_pk_add_f32 v[112:113], v[104:105], v[112:113]
	v_pk_add_f32 v[110:111], v[102:103], v[118:119]

; __device__ __forceinline__ unsigned pk2(float lo, float hi) { const f32x2_t v = {lo, hi}; const bf16x2_t b = __builtin_convertvector(v, bf16x2_t); return __builtin_bit_cast(unsigned, b); }
; __device__ __forceinline__ float lo16(unsigned w) { return __uint_as_float(w << 16); }
; __device__ __forceinline__ float hi16(unsigned w) { return __uint_as_float(w & 0xffff0000u); }
;     __device__ __forceinline__ void operator()(const f32x4 (&acc)[2][2][4][2], const Unit& u, int wr, int wc, int fr, int fq) const {
;     ...
;                 const int rl = rloc + ai * HALF + m * 16;
;                 const unsigned char* gp_ = (const unsigned char*)(Gp + (size_t)(u.pm * BM + rl) * ldg) + colg;
; #pragma unroll
;                 for (int bj = 0; bj < 2; ++bj) {
;                     const u32x2 gp = *(const u32x2*)(gp_ + bj * HALF);
;                     const f32x4 v0 = acc[ai][bj][m][0] * (1.0f / 255.0f), v1 = acc[ai][bj][m][1] * (1.0f / 255.0f);
;                     f32x4 z0 = {(float)(gp.x & 255u) * v0[0], (float)((gp.x >> 8) & 255u) * v0[1], (float)((gp.x >> 16) & 255u) * v0[2], (float)(gp.x >> 24) * v0[3]};
;                     f32x4 z1 = {(float)(gp.y & 255u) * v1[0], (float)((gp.y >> 8) & 255u) * v1[1], (float)((gp.y >> 16) & 255u) * v1[2], (float)(gp.y >> 24) * v1[3]};
;                     if (ctx) {
;                         float* pp = part + ((size_t)(b * 256 + rl)) * D + colm + bj * HALF;
;                         *(f32x4*)pp = z0; *(f32x4*)(pp + 4) = z1;
;                     } else {
;                         bf16_t* mp = MG + (size_t)(u.pm * BM + rl) * D + colm + bj * HALF;
;                         if (b != 0) { const u32x4 pv = *(const u32x4*)mp;
;                             z0 += (f32x4){lo16(pv.x), hi16(pv.x), lo16(pv.y), hi16(pv.y)}; z1 += (f32x4){lo16(pv.z), hi16(pv.z), lo16(pv.w), hi16(pv.w)}; }
;                         u32x4 w; w.x = pk2(z0[0], z0[1]); w.y = pk2(z0[2], z0[3]); w.z = pk2(z1[0], z1[1]); w.w = pk2(z1[2], z1[3]);
;                         *(u32x4*)mp = w;
.LBB0_214:
	s_nop 0
	v_add_u32_e32 v98, s7, v169
	v_mov_b64_e32 v[100:101], s[90:91]
	v_mad_i64_i32 v[100:101], s[22:23], v98, s21, v[100:101]
	v_lshl_add_u64 v[106:107], v[100:101], 0, v[146:147]
	s_nop 0
	v_ashrrev_i32_e32 v99, 31, v98
	v_pk_mul_f32 v[96:97], v[96:97], s[96:97] op_sel_hi:[1,0]
	v_pk_mul_f32 v[94:95], v[94:95], s[96:97] op_sel_hi:[1,0]
	v_pk_mul_f32 v[102:103], v[92:93], s[96:97] op_sel_hi:[1,0]
	v_pk_mul_f32 v[104:105], v[90:91], s[96:97] op_sel_hi:[1,0]
	v_lshlrev_b64 v[98:99], 11, v[98:99]
	s_mov_b64 s[58:59], -1
	s_and_b64 vcc, exec, s[46:47]
	v_lshl_add_u64 v[108:109], s[84:85], 0, v[98:99]
	s_nop 0
	v_cvt_f32_ubyte1_e32 v91, v226
	v_cvt_f32_ubyte0_e32 v90, v226
	v_cvt_f32_ubyte3_e32 v93, v226
	v_cvt_f32_ubyte2_e32 v92, v226
	v_pk_mul_f32 v[92:93], v[96:97], v[92:93]
	v_pk_mul_f32 v[90:91], v[94:95], v[90:91]
	v_cvt_f32_ubyte1_e32 v95, v227
	v_cvt_f32_ubyte0_e32 v94, v227
	v_cvt_f32_ubyte3_e32 v97, v227
	v_cvt_f32_ubyte2_e32 v96, v227
	v_pk_mul_f32 v[96:97], v[102:103], v[96:97]
	v_pk_mul_f32 v[94:95], v[104:105], v[94:95]
	s_cbranch_vccnz .LBB0_218
	v_mov_b64_e32 v[104:105], v[96:97]
	v_mov_b64_e32 v[100:101], v[92:93]
	v_lshl_add_u64 v[110:111], v[108:109], 0, v[0:1]
	s_and_b64 vcc, exec, s[4:5]
	v_mov_b64_e32 v[102:103], v[94:95]
	v_mov_b64_e32 v[98:99], v[90:91]
	s_cbranch_vccnz .LBB0_217
	global_load_dwordx4 v[98:101], v[110:111], off
	s_waitcnt vmcnt(0)
	v_lshlrev_b32_e32 v102, 16, v98
	v_and_b32_e32 v103, 0xffff0000, v98
	v_lshlrev_b32_e32 v98, 16, v99
	v_and_b32_e32 v99, 0xffff0000, v99
	v_lshlrev_b32_e32 v112, 16, v100
	v_and_b32_e32 v113, 0xffff0000, v100
	v_lshlrev_b32_e32 v104, 16, v101
	v_and_b32_e32 v105, 0xffff0000, v101
	v_pk_add_f32 v[100:101], v[92:93], v[98:99]
	v_pk_add_f32 v[98:99], v[90:91], v[102:103]
	v_pk_add_f32 v[104:105], v[96:97], v[104:105]
	v_pk_add_f32 v[102:103], v[94:95], v[112:113]

; __device__ __forceinline__ unsigned pk2(float lo, float hi) { const f32x2_t v = {lo, hi}; const bf16x2_t b = __builtin_convertvector(v, bf16x2_t); return __builtin_bit_cast(unsigned, b); }
; __device__ __forceinline__ float lo16(unsigned w) { return __uint_as_float(w << 16); }
; __device__ __forceinline__ float hi16(unsigned w) { return __uint_as_float(w & 0xffff0000u); }
;     __device__ __forceinline__ void operator()(const f32x4 (&acc)[2][2][4][2], const Unit& u, int wr, int wc, int fr, int fq) const {
;     ...
;                     const u32x2 gp = *(const u32x2*)(gp_ + bj * HALF);
;                     const f32x4 v0 = acc[ai][bj][m][0] * (1.0f / 255.0f), v1 = acc[ai][bj][m][1] * (1.0f / 255.0f);
;                     f32x4 z0 = {(float)(gp.x & 255u) * v0[0], (float)((gp.x >> 8) & 255u) * v0[1], (float)((gp.x >> 16) & 255u) * v0[2], (float)(gp.x >> 24) * v0[3]};
;                     f32x4 z1 = {(float)(gp.y & 255u) * v1[0], (float)((gp.y >> 8) & 255u) * v1[1], (float)((gp.y >> 16) & 255u) * v1[2], (float)(gp.y >> 24) * v1[3]};
;                     if (ctx) {
;                         float* pp = part + ((size_t)(b * 256 + rl)) * D + colm + bj * HALF;
;                         *(f32x4*)pp = z0; *(f32x4*)(pp + 4) = z1;
;                     } else {
;                         bf16_t* mp = MG + (size_t)(u.pm * BM + rl) * D + colm + bj * HALF;
;                         if (b != 0) { const u32x4 pv = *(const u32x4*)mp;
;                             z0 += (f32x4){lo16(pv.x), hi16(pv.x), lo16(pv.y), hi16(pv.y)}; z1 += (f32x4){lo16(pv.z), hi16(pv.z), lo16(pv.w), hi16(pv.w)}; }
;                         u32x4 w; w.x = pk2(z0[0], z0[1]); w.y = pk2(z0[2], z0[3]); w.z = pk2(z1[0], z1[1]); w.w = pk2(z1[2], z1[3]);
;                         *(u32x4*)mp = w;
.LBB0_220:
	s_nop 0
	v_pk_mul_f32 v[88:89], v[88:89], s[96:97] op_sel_hi:[1,0]
	v_pk_mul_f32 v[86:87], v[86:87], s[96:97] op_sel_hi:[1,0]
	v_pk_mul_f32 v[92:93], v[84:85], s[96:97] op_sel_hi:[1,0]
	v_pk_mul_f32 v[94:95], v[82:83], s[96:97] op_sel_hi:[1,0]
	s_mov_b64 s[58:59], -1
	s_and_b64 vcc, exec, s[46:47]
	s_nop 0
	v_cvt_f32_ubyte1_e32 v83, v228
	v_cvt_f32_ubyte0_e32 v82, v228
	v_cvt_f32_ubyte3_e32 v85, v228
	v_cvt_f32_ubyte2_e32 v84, v228
	v_pk_mul_f32 v[84:85], v[88:89], v[84:85]
	v_pk_mul_f32 v[82:83], v[86:87], v[82:83]
	v_cvt_f32_ubyte1_e32 v87, v229
	v_cvt_f32_ubyte0_e32 v86, v229
	v_cvt_f32_ubyte3_e32 v89, v229
	v_cvt_f32_ubyte2_e32 v88, v229
	v_pk_mul_f32 v[88:89], v[92:93], v[88:89]
	v_pk_mul_f32 v[86:87], v[94:95], v[86:87]
	s_cbranch_vccnz .LBB0_224
	v_mov_b64_e32 v[96:97], v[88:89]
	v_mov_b64_e32 v[92:93], v[84:85]
	v_lshl_add_u64 v[100:101], v[108:109], 0, v[0:1]
	s_and_b64 vcc, exec, s[4:5]
	v_mov_b64_e32 v[94:95], v[86:87]
	v_mov_b64_e32 v[90:91], v[82:83]
	s_cbranch_vccnz .LBB0_223
	global_load_dwordx4 v[90:93], v[100:101], off offset:256
	s_waitcnt vmcnt(0)
	v_lshlrev_b32_e32 v94, 16, v90
	v_and_b32_e32 v95, 0xffff0000, v90
	v_lshlrev_b32_e32 v90, 16, v91
	v_and_b32_e32 v91, 0xffff0000, v91
	v_lshlrev_b32_e32 v102, 16, v92
	v_and_b32_e32 v103, 0xffff0000, v92
	v_lshlrev_b32_e32 v96, 16, v93
	v_and_b32_e32 v97, 0xffff0000, v93
	v_pk_add_f32 v[92:93], v[84:85], v[90:91]
	v_pk_add_f32 v[90:91], v[82:83], v[94:95]
	v_pk_add_f32 v[96:97], v[88:89], v[96:97]
	v_pk_add_f32 v[94:95], v[86:87], v[102:103]

; __device__ __forceinline__ unsigned pk2(float lo, float hi) { const f32x2_t v = {lo, hi}; const bf16x2_t b = __builtin_convertvector(v, bf16x2_t); return __builtin_bit_cast(unsigned, b); }
; __device__ __forceinline__ float lo16(unsigned w) { return __uint_as_float(w << 16); }
; __device__ __forceinline__ float hi16(unsigned w) { return __uint_as_float(w & 0xffff0000u); }
;     __device__ __forceinline__ void operator()(const f32x4 (&acc)[2][2][4][2], const Unit& u, int wr, int wc, int fr, int fq) const {
;     ...
;                 const int rl = rloc + ai * HALF + m * 16;
;                 const unsigned char* gp_ = (const unsigned char*)(Gp + (size_t)(u.pm * BM + rl) * ldg) + colg;
; #pragma unroll
;                 for (int bj = 0; bj < 2; ++bj) {
;                     const u32x2 gp = *(const u32x2*)(gp_ + bj * HALF);
;                     const f32x4 v0 = acc[ai][bj][m][0] * (1.0f / 255.0f), v1 = acc[ai][bj][m][1] * (1.0f / 255.0f);
;                     f32x4 z0 = {(float)(gp.x & 255u) * v0[0], (float)((gp.x >> 8) & 255u) * v0[1], (float)((gp.x >> 16) & 255u) * v0[2], (float)(gp.x >> 24) * v0[3]};
;                     f32x4 z1 = {(float)(gp.y & 255u) * v1[0], (float)((gp.y >> 8) & 255u) * v1[1], (float)((gp.y >> 16) & 255u) * v1[2], (float)(gp.y >> 24) * v1[3]};
;                     if (ctx) {
;                         float* pp = part + ((size_t)(b * 256 + rl)) * D + colm + bj * HALF;
;                         *(f32x4*)pp = z0; *(f32x4*)(pp + 4) = z1;
;                     } else {
;                         bf16_t* mp = MG + (size_t)(u.pm * BM + rl) * D + colm + bj * HALF;
;                         if (b != 0) { const u32x4 pv = *(const u32x4*)mp;
;                             z0 += (f32x4){lo16(pv.x), hi16(pv.x), lo16(pv.y), hi16(pv.y)}; z1 += (f32x4){lo16(pv.z), hi16(pv.z), lo16(pv.w), hi16(pv.w)}; }
;                         u32x4 w; w.x = pk2(z0[0], z0[1]); w.y = pk2(z0[2], z0[3]); w.z = pk2(z1[0], z1[1]); w.w = pk2(z1[2], z1[3]);
;                         *(u32x4*)mp = w;
.LBB0_226:
	s_nop 0
	v_add_u32_e32 v82, s7, v170
	v_mov_b64_e32 v[84:85], s[90:91]
	v_mad_i64_i32 v[84:85], s[22:23], v82, s21, v[84:85]
	v_lshl_add_u64 v[90:91], v[84:85], 0, v[146:147]
	s_nop 0
	v_ashrrev_i32_e32 v83, 31, v82
	v_pk_mul_f32 v[80:81], v[80:81], s[96:97] op_sel_hi:[1,0]
	v_pk_mul_f32 v[78:79], v[78:79], s[96:97] op_sel_hi:[1,0]
	v_pk_mul_f32 v[86:87], v[76:77], s[96:97] op_sel_hi:[1,0]
	v_pk_mul_f32 v[88:89], v[74:75], s[96:97] op_sel_hi:[1,0]
	v_lshlrev_b64 v[82:83], 11, v[82:83]
	s_mov_b64 s[58:59], -1
	s_and_b64 vcc, exec, s[46:47]
	v_lshl_add_u64 v[92:93], s[84:85], 0, v[82:83]
	s_nop 0
	v_cvt_f32_ubyte1_e32 v75, v230
	v_cvt_f32_ubyte0_e32 v74, v230
	v_cvt_f32_ubyte3_e32 v77, v230
	v_cvt_f32_ubyte2_e32 v76, v230
	v_pk_mul_f32 v[76:77], v[80:81], v[76:77]
	v_pk_mul_f32 v[74:75], v[78:79], v[74:75]
	v_cvt_f32_ubyte1_e32 v79, v231
	v_cvt_f32_ubyte0_e32 v78, v231
	v_cvt_f32_ubyte3_e32 v81, v231
	v_cvt_f32_ubyte2_e32 v80, v231
	v_pk_mul_f32 v[80:81], v[86:87], v[80:81]
	v_pk_mul_f32 v[78:79], v[88:89], v[78:79]
	s_cbranch_vccnz .LBB0_230
	v_mov_b64_e32 v[88:89], v[80:81]
	v_mov_b64_e32 v[84:85], v[76:77]
	v_lshl_add_u64 v[94:95], v[92:93], 0, v[0:1]
	s_and_b64 vcc, exec, s[4:5]
	v_mov_b64_e32 v[86:87], v[78:79]
	v_mov_b64_e32 v[82:83], v[74:75]
	s_cbranch_vccnz .LBB0_229
	global_load_dwordx4 v[82:85], v[94:95], off
	s_waitcnt vmcnt(0)
	v_lshlrev_b32_e32 v86, 16, v82
	v_and_b32_e32 v87, 0xffff0000, v82
	v_lshlrev_b32_e32 v82, 16, v83
	v_and_b32_e32 v83, 0xffff0000, v83
	v_lshlrev_b32_e32 v96, 16, v84
	v_and_b32_e32 v97, 0xffff0000, v84
	v_lshlrev_b32_e32 v88, 16, v85
	v_and_b32_e32 v89, 0xffff0000, v85
	v_pk_add_f32 v[84:85], v[76:77], v[82:83]
	v_pk_add_f32 v[82:83], v[74:75], v[86:87]
	v_pk_add_f32 v[88:89], v[80:81], v[88:89]
	v_pk_add_f32 v[86:87], v[78:79], v[96:97]

; __device__ __forceinline__ unsigned pk2(float lo, float hi) { const f32x2_t v = {lo, hi}; const bf16x2_t b = __builtin_convertvector(v, bf16x2_t); return __builtin_bit_cast(unsigned, b); }
; __device__ __forceinline__ float lo16(unsigned w) { return __uint_as_float(w << 16); }
; __device__ __forceinline__ float hi16(unsigned w) { return __uint_as_float(w & 0xffff0000u); }
;     __device__ __forceinline__ void operator()(const f32x4 (&acc)[2][2][4][2], const Unit& u, int wr, int wc, int fr, int fq) const {
;     ...
;                     const u32x2 gp = *(const u32x2*)(gp_ + bj * HALF);
;                     const f32x4 v0 = acc[ai][bj][m][0] * (1.0f / 255.0f), v1 = acc[ai][bj][m][1] * (1.0f / 255.0f);
;                     f32x4 z0 = {(float)(gp.x & 255u) * v0[0], (float)((gp.x >> 8) & 255u) * v0[1], (float)((gp.x >> 16) & 255u) * v0[2], (float)(gp.x >> 24) * v0[3]};
;                     f32x4 z1 = {(float)(gp.y & 255u) * v1[0], (float)((gp.y >> 8) & 255u) * v1[1], (float)((gp.y >> 16) & 255u) * v1[2], (float)(gp.y >> 24) * v1[3]};
;                     if (ctx) {
;                         float* pp = part + ((size_t)(b * 256 + rl)) * D + colm + bj * HALF;
;                         *(f32x4*)pp = z0; *(f32x4*)(pp + 4) = z1;
;                     } else {
;                         bf16_t* mp = MG + (size_t)(u.pm * BM + rl) * D + colm + bj * HALF;
;                         if (b != 0) { const u32x4 pv = *(const u32x4*)mp;
;                             z0 += (f32x4){lo16(pv.x), hi16(pv.x), lo16(pv.y), hi16(pv.y)}; z1 += (f32x4){lo16(pv.z), hi16(pv.z), lo16(pv.w), hi16(pv.w)}; }
;                         u32x4 w; w.x = pk2(z0[0], z0[1]); w.y = pk2(z0[2], z0[3]); w.z = pk2(z1[0], z1[1]); w.w = pk2(z1[2], z1[3]);
;                         *(u32x4*)mp = w;
.LBB0_232:
	s_nop 0
	v_pk_mul_f32 v[72:73], v[72:73], s[96:97] op_sel_hi:[1,0]
	v_pk_mul_f32 v[70:71], v[70:71], s[96:97] op_sel_hi:[1,0]
	v_pk_mul_f32 v[76:77], v[68:69], s[96:97] op_sel_hi:[1,0]
	v_pk_mul_f32 v[78:79], v[66:67], s[96:97] op_sel_hi:[1,0]
	s_mov_b64 s[58:59], -1
	s_and_b64 vcc, exec, s[46:47]
	s_nop 0
	v_cvt_f32_ubyte1_e32 v67, v232
	v_cvt_f32_ubyte0_e32 v66, v232
	v_cvt_f32_ubyte3_e32 v69, v232
	v_cvt_f32_ubyte2_e32 v68, v232
	v_pk_mul_f32 v[68:69], v[72:73], v[68:69]
	v_pk_mul_f32 v[66:67], v[70:71], v[66:67]
	v_cvt_f32_ubyte1_e32 v71, v233
	v_cvt_f32_ubyte0_e32 v70, v233
	v_cvt_f32_ubyte3_e32 v73, v233
	v_cvt_f32_ubyte2_e32 v72, v233
	v_pk_mul_f32 v[72:73], v[76:77], v[72:73]
	v_pk_mul_f32 v[70:71], v[78:79], v[70:71]
	s_cbranch_vccnz .LBB0_236
	v_mov_b64_e32 v[80:81], v[72:73]
	v_mov_b64_e32 v[76:77], v[68:69]
	v_lshl_add_u64 v[84:85], v[92:93], 0, v[0:1]
	s_and_b64 vcc, exec, s[4:5]
	v_mov_b64_e32 v[78:79], v[70:71]
	v_mov_b64_e32 v[74:75], v[66:67]
	s_cbranch_vccnz .LBB0_235
	global_load_dwordx4 v[74:77], v[84:85], off offset:256
	s_waitcnt vmcnt(0)
	v_lshlrev_b32_e32 v78, 16, v74
	v_and_b32_e32 v79, 0xffff0000, v74
	v_lshlrev_b32_e32 v74, 16, v75
	v_and_b32_e32 v75, 0xffff0000, v75
	v_lshlrev_b32_e32 v86, 16, v76
	v_and_b32_e32 v87, 0xffff0000, v76
	v_lshlrev_b32_e32 v80, 16, v77
	v_and_b32_e32 v81, 0xffff0000, v77
	v_pk_add_f32 v[76:77], v[68:69], v[74:75]
	v_pk_add_f32 v[74:75], v[66:67], v[78:79]
	v_pk_add_f32 v[80:81], v[72:73], v[80:81]
	v_pk_add_f32 v[78:79], v[70:71], v[86:87]

; __device__ __forceinline__ unsigned pk2(float lo, float hi) { const f32x2_t v = {lo, hi}; const bf16x2_t b = __builtin_convertvector(v, bf16x2_t); return __builtin_bit_cast(unsigned, b); }
; __device__ __forceinline__ float lo16(unsigned w) { return __uint_as_float(w << 16); }
; __device__ __forceinline__ float hi16(unsigned w) { return __uint_as_float(w & 0xffff0000u); }
;     __device__ __forceinline__ void operator()(const f32x4 (&acc)[2][2][4][2], const Unit& u, int wr, int wc, int fr, int fq) const {
;     ...
;                 const int rl = rloc + ai * HALF + m * 16;
;                 const unsigned char* gp_ = (const unsigned char*)(Gp + (size_t)(u.pm * BM + rl) * ldg) + colg;
; #pragma unroll
;                 for (int bj = 0; bj < 2; ++bj) {
;                     const u32x2 gp = *(const u32x2*)(gp_ + bj * HALF);
;                     const f32x4 v0 = acc[ai][bj][m][0] * (1.0f / 255.0f), v1 = acc[ai][bj][m][1] * (1.0f / 255.0f);
;                     f32x4 z0 = {(float)(gp.x & 255u) * v0[0], (float)((gp.x >> 8) & 255u) * v0[1], (float)((gp.x >> 16) & 255u) * v0[2], (float)(gp.x >> 24) * v0[3]};
;                     f32x4 z1 = {(float)(gp.y & 255u) * v1[0], (float)((gp.y >> 8) & 255u) * v1[1], (float)((gp.y >> 16) & 255u) * v1[2], (float)(gp.y >> 24) * v1[3]};
;                     if (ctx) {
;                         float* pp = part + ((size_t)(b * 256 + rl)) * D + colm + bj * HALF;
;                         *(f32x4*)pp = z0; *(f32x4*)(pp + 4) = z1;
;                     } else {
;                         bf16_t* mp = MG + (size_t)(u.pm * BM + rl) * D + colm + bj * HALF;
;                         if (b != 0) { const u32x4 pv = *(const u32x4*)mp;
;                             z0 += (f32x4){lo16(pv.x), hi16(pv.x), lo16(pv.y), hi16(pv.y)}; z1 += (f32x4){lo16(pv.z), hi16(pv.z), lo16(pv.w), hi16(pv.w)}; }
;                         u32x4 w; w.x = pk2(z0[0], z0[1]); w.y = pk2(z0[2], z0[3]); w.z = pk2(z1[0], z1[1]); w.w = pk2(z1[2], z1[3]);
;                         *(u32x4*)mp = w;
.LBB0_238:
	s_nop 0
	v_add_u32_e32 v66, s7, v171
	v_mov_b64_e32 v[68:69], s[90:91]
	v_mad_i64_i32 v[68:69], s[22:23], v66, s21, v[68:69]
	v_lshl_add_u64 v[74:75], v[68:69], 0, v[146:147]
	s_nop 0
	v_ashrrev_i32_e32 v67, 31, v66
	v_pk_mul_f32 v[64:65], v[64:65], s[96:97] op_sel_hi:[1,0]
	v_pk_mul_f32 v[62:63], v[62:63], s[96:97] op_sel_hi:[1,0]
	v_pk_mul_f32 v[70:71], v[60:61], s[96:97] op_sel_hi:[1,0]
	v_pk_mul_f32 v[72:73], v[58:59], s[96:97] op_sel_hi:[1,0]
	v_lshlrev_b64 v[66:67], 11, v[66:67]
	s_mov_b64 s[58:59], -1
	s_and_b64 vcc, exec, s[46:47]
	v_lshl_add_u64 v[76:77], s[84:85], 0, v[66:67]
	s_nop 0
	v_cvt_f32_ubyte1_e32 v59, v234
	v_cvt_f32_ubyte0_e32 v58, v234
	v_cvt_f32_ubyte3_e32 v61, v234
	v_cvt_f32_ubyte2_e32 v60, v234
	v_pk_mul_f32 v[60:61], v[64:65], v[60:61]
	v_pk_mul_f32 v[58:59], v[62:63], v[58:59]
	v_cvt_f32_ubyte1_e32 v63, v235
	v_cvt_f32_ubyte0_e32 v62, v235
	v_cvt_f32_ubyte3_e32 v65, v235
	v_cvt_f32_ubyte2_e32 v64, v235
	v_pk_mul_f32 v[64:65], v[70:71], v[64:65]
	v_pk_mul_f32 v[62:63], v[72:73], v[62:63]
	s_cbranch_vccnz .LBB0_242
	v_mov_b64_e32 v[72:73], v[64:65]
	v_mov_b64_e32 v[68:69], v[60:61]
	v_lshl_add_u64 v[78:79], v[76:77], 0, v[0:1]
	s_and_b64 vcc, exec, s[4:5]
	v_mov_b64_e32 v[70:71], v[62:63]
	v_mov_b64_e32 v[66:67], v[58:59]
	s_cbranch_vccnz .LBB0_241
	global_load_dwordx4 v[66:69], v[78:79], off
	s_waitcnt vmcnt(0)
	v_lshlrev_b32_e32 v70, 16, v66
	v_and_b32_e32 v71, 0xffff0000, v66
	v_lshlrev_b32_e32 v66, 16, v67
	v_and_b32_e32 v67, 0xffff0000, v67
	v_lshlrev_b32_e32 v80, 16, v68
	v_and_b32_e32 v81, 0xffff0000, v68
	v_lshlrev_b32_e32 v72, 16, v69
	v_and_b32_e32 v73, 0xffff0000, v69
	v_pk_add_f32 v[68:69], v[60:61], v[66:67]
	v_pk_add_f32 v[66:67], v[58:59], v[70:71]
	v_pk_add_f32 v[72:73], v[64:65], v[72:73]
	v_pk_add_f32 v[70:71], v[62:63], v[80:81]

; __device__ __forceinline__ unsigned pk2(float lo, float hi) { const f32x2_t v = {lo, hi}; const bf16x2_t b = __builtin_convertvector(v, bf16x2_t); return __builtin_bit_cast(unsigned, b); }
; __device__ __forceinline__ float lo16(unsigned w) { return __uint_as_float(w << 16); }
; __device__ __forceinline__ float hi16(unsigned w) { return __uint_as_float(w & 0xffff0000u); }
;     __device__ __forceinline__ void operator()(const f32x4 (&acc)[2][2][4][2], const Unit& u, int wr, int wc, int fr, int fq) const {
;     ...
;                     const u32x2 gp = *(const u32x2*)(gp_ + bj * HALF);
;                     const f32x4 v0 = acc[ai][bj][m][0] * (1.0f / 255.0f), v1 = acc[ai][bj][m][1] * (1.0f / 255.0f);
;                     f32x4 z0 = {(float)(gp.x & 255u) * v0[0], (float)((gp.x >> 8) & 255u) * v0[1], (float)((gp.x >> 16) & 255u) * v0[2], (float)(gp.x >> 24) * v0[3]};
;                     f32x4 z1 = {(float)(gp.y & 255u) * v1[0], (float)((gp.y >> 8) & 255u) * v1[1], (float)((gp.y >> 16) & 255u) * v1[2], (float)(gp.y >> 24) * v1[3]};
;                     if (ctx) {
;                         float* pp = part + ((size_t)(b * 256 + rl)) * D + colm + bj * HALF;
;                         *(f32x4*)pp = z0; *(f32x4*)(pp + 4) = z1;
;                     } else {
;                         bf16_t* mp = MG + (size_t)(u.pm * BM + rl) * D + colm + bj * HALF;
;                         if (b != 0) { const u32x4 pv = *(const u32x4*)mp;
;                             z0 += (f32x4){lo16(pv.x), hi16(pv.x), lo16(pv.y), hi16(pv.y)}; z1 += (f32x4){lo16(pv.z), hi16(pv.z), lo16(pv.w), hi16(pv.w)}; }
;                         u32x4 w; w.x = pk2(z0[0], z0[1]); w.y = pk2(z0[2], z0[3]); w.z = pk2(z1[0], z1[1]); w.w = pk2(z1[2], z1[3]);
;                         *(u32x4*)mp = w;
.LBB0_244:
	s_nop 0
	v_pk_mul_f32 v[56:57], v[56:57], s[96:97] op_sel_hi:[1,0]
	v_pk_mul_f32 v[54:55], v[54:55], s[96:97] op_sel_hi:[1,0]
	v_pk_mul_f32 v[60:61], v[52:53], s[96:97] op_sel_hi:[1,0]
	v_pk_mul_f32 v[62:63], v[50:51], s[96:97] op_sel_hi:[1,0]
	s_mov_b64 s[58:59], -1
	s_and_b64 vcc, exec, s[46:47]
	s_nop 0
	v_cvt_f32_ubyte1_e32 v51, v236
	v_cvt_f32_ubyte0_e32 v50, v236
	v_cvt_f32_ubyte3_e32 v53, v236
	v_cvt_f32_ubyte2_e32 v52, v236
	v_pk_mul_f32 v[52:53], v[56:57], v[52:53]
	v_pk_mul_f32 v[50:51], v[54:55], v[50:51]
	v_cvt_f32_ubyte1_e32 v55, v237
	v_cvt_f32_ubyte0_e32 v54, v237
	v_cvt_f32_ubyte3_e32 v57, v237
	v_cvt_f32_ubyte2_e32 v56, v237
	v_pk_mul_f32 v[56:57], v[60:61], v[56:57]
	v_pk_mul_f32 v[54:55], v[62:63], v[54:55]
	s_cbranch_vccnz .LBB0_248
	v_mov_b64_e32 v[64:65], v[56:57]
	v_mov_b64_e32 v[60:61], v[52:53]
	v_lshl_add_u64 v[68:69], v[76:77], 0, v[0:1]
	s_and_b64 vcc, exec, s[4:5]
	v_mov_b64_e32 v[62:63], v[54:55]
	v_mov_b64_e32 v[58:59], v[50:51]
	s_cbranch_vccnz .LBB0_247
	global_load_dwordx4 v[58:61], v[68:69], off offset:256
	s_waitcnt vmcnt(0)
	v_lshlrev_b32_e32 v62, 16, v58
	v_and_b32_e32 v63, 0xffff0000, v58
	v_lshlrev_b32_e32 v58, 16, v59
	v_and_b32_e32 v59, 0xffff0000, v59
	v_lshlrev_b32_e32 v70, 16, v60
	v_and_b32_e32 v71, 0xffff0000, v60
	v_lshlrev_b32_e32 v64, 16, v61
	v_and_b32_e32 v65, 0xffff0000, v61
	v_pk_add_f32 v[60:61], v[52:53], v[58:59]
	v_pk_add_f32 v[58:59], v[50:51], v[62:63]
	v_pk_add_f32 v[64:65], v[56:57], v[64:65]
	v_pk_add_f32 v[62:63], v[54:55], v[70:71]

; __device__ __forceinline__ unsigned pk2(float lo, float hi) { const f32x2_t v = {lo, hi}; const bf16x2_t b = __builtin_convertvector(v, bf16x2_t); return __builtin_bit_cast(unsigned, b); }
; __device__ __forceinline__ float lo16(unsigned w) { return __uint_as_float(w << 16); }
; __device__ __forceinline__ float hi16(unsigned w) { return __uint_as_float(w & 0xffff0000u); }
;     __device__ __forceinline__ void operator()(const f32x4 (&acc)[2][2][4][2], const Unit& u, int wr, int wc, int fr, int fq) const {
;     ...
;                 const int rl = rloc + ai * HALF + m * 16;
;                 const unsigned char* gp_ = (const unsigned char*)(Gp + (size_t)(u.pm * BM + rl) * ldg) + colg;
; #pragma unroll
;                 for (int bj = 0; bj < 2; ++bj) {
;                     const u32x2 gp = *(const u32x2*)(gp_ + bj * HALF);
;                     const f32x4 v0 = acc[ai][bj][m][0] * (1.0f / 255.0f), v1 = acc[ai][bj][m][1] * (1.0f / 255.0f);
;                     f32x4 z0 = {(float)(gp.x & 255u) * v0[0], (float)((gp.x >> 8) & 255u) * v0[1], (float)((gp.x >> 16) & 255u) * v0[2], (float)(gp.x >> 24) * v0[3]};
;                     f32x4 z1 = {(float)(gp.y & 255u) * v1[0], (float)((gp.y >> 8) & 255u) * v1[1], (float)((gp.y >> 16) & 255u) * v1[2], (float)(gp.y >> 24) * v1[3]};
;                     if (ctx) {
;                         float* pp = part + ((size_t)(b * 256 + rl)) * D + colm + bj * HALF;
;                         *(f32x4*)pp = z0; *(f32x4*)(pp + 4) = z1;
;                     } else {
;                         bf16_t* mp = MG + (size_t)(u.pm * BM + rl) * D + colm + bj * HALF;
;                         if (b != 0) { const u32x4 pv = *(const u32x4*)mp;
;                             z0 += (f32x4){lo16(pv.x), hi16(pv.x), lo16(pv.y), hi16(pv.y)}; z1 += (f32x4){lo16(pv.z), hi16(pv.z), lo16(pv.w), hi16(pv.w)}; }
;                         u32x4 w; w.x = pk2(z0[0], z0[1]); w.y = pk2(z0[2], z0[3]); w.z = pk2(z1[0], z1[1]); w.w = pk2(z1[2], z1[3]);
;                         *(u32x4*)mp = w;
.LBB0_250:
	s_nop 0
	v_add_u32_e32 v50, s7, v172
	v_mov_b64_e32 v[52:53], s[90:91]
	v_mad_i64_i32 v[52:53], s[22:23], v50, s21, v[52:53]
	v_lshl_add_u64 v[58:59], v[52:53], 0, v[146:147]
	s_nop 0
	v_ashrrev_i32_e32 v51, 31, v50
	v_pk_mul_f32 v[48:49], v[48:49], s[96:97] op_sel_hi:[1,0]
	v_pk_mul_f32 v[46:47], v[46:47], s[96:97] op_sel_hi:[1,0]
	v_pk_mul_f32 v[54:55], v[44:45], s[96:97] op_sel_hi:[1,0]
	v_pk_mul_f32 v[56:57], v[42:43], s[96:97] op_sel_hi:[1,0]
	v_lshlrev_b64 v[50:51], 11, v[50:51]
	s_mov_b64 s[58:59], -1
	s_and_b64 vcc, exec, s[46:47]
	v_lshl_add_u64 v[60:61], s[84:85], 0, v[50:51]
	s_nop 0
	v_cvt_f32_ubyte1_e32 v43, v238
	v_cvt_f32_ubyte0_e32 v42, v238
	v_cvt_f32_ubyte3_e32 v45, v238
	v_cvt_f32_ubyte2_e32 v44, v238
	v_pk_mul_f32 v[44:45], v[48:49], v[44:45]
	v_pk_mul_f32 v[42:43], v[46:47], v[42:43]
	v_cvt_f32_ubyte1_e32 v47, v239
	v_cvt_f32_ubyte0_e32 v46, v239
	v_cvt_f32_ubyte3_e32 v49, v239
	v_cvt_f32_ubyte2_e32 v48, v239
	v_pk_mul_f32 v[48:49], v[54:55], v[48:49]
	v_pk_mul_f32 v[46:47], v[56:57], v[46:47]
	s_cbranch_vccnz .LBB0_254
	v_mov_b64_e32 v[56:57], v[48:49]
	v_mov_b64_e32 v[52:53], v[44:45]
	v_lshl_add_u64 v[62:63], v[60:61], 0, v[0:1]
	s_and_b64 vcc, exec, s[4:5]
	v_mov_b64_e32 v[54:55], v[46:47]
	v_mov_b64_e32 v[50:51], v[42:43]
	s_cbranch_vccnz .LBB0_253
	global_load_dwordx4 v[50:53], v[62:63], off
	s_waitcnt vmcnt(0)
	v_lshlrev_b32_e32 v54, 16, v50
	v_and_b32_e32 v55, 0xffff0000, v50
	v_lshlrev_b32_e32 v50, 16, v51
	v_and_b32_e32 v51, 0xffff0000, v51
	v_lshlrev_b32_e32 v64, 16, v52
	v_and_b32_e32 v65, 0xffff0000, v52
	v_lshlrev_b32_e32 v56, 16, v53
	v_and_b32_e32 v57, 0xffff0000, v53
	v_pk_add_f32 v[52:53], v[44:45], v[50:51]
	v_pk_add_f32 v[50:51], v[42:43], v[54:55]
	v_pk_add_f32 v[56:57], v[48:49], v[56:57]
	v_pk_add_f32 v[54:55], v[46:47], v[64:65]

; __device__ __forceinline__ unsigned pk2(float lo, float hi) { const f32x2_t v = {lo, hi}; const bf16x2_t b = __builtin_convertvector(v, bf16x2_t); return __builtin_bit_cast(unsigned, b); }
; __device__ __forceinline__ float lo16(unsigned w) { return __uint_as_float(w << 16); }
; __device__ __forceinline__ float hi16(unsigned w) { return __uint_as_float(w & 0xffff0000u); }
;     __device__ __forceinline__ void operator()(const f32x4 (&acc)[2][2][4][2], const Unit& u, int wr, int wc, int fr, int fq) const {
;     ...
;                     const u32x2 gp = *(const u32x2*)(gp_ + bj * HALF);
;                     const f32x4 v0 = acc[ai][bj][m][0] * (1.0f / 255.0f), v1 = acc[ai][bj][m][1] * (1.0f / 255.0f);
;                     f32x4 z0 = {(float)(gp.x & 255u) * v0[0], (float)((gp.x >> 8) & 255u) * v0[1], (float)((gp.x >> 16) & 255u) * v0[2], (float)(gp.x >> 24) * v0[3]};
;                     f32x4 z1 = {(float)(gp.y & 255u) * v1[0], (float)((gp.y >> 8) & 255u) * v1[1], (float)((gp.y >> 16) & 255u) * v1[2], (float)(gp.y >> 24) * v1[3]};
;                     if (ctx) {
;                         float* pp = part + ((size_t)(b * 256 + rl)) * D + colm + bj * HALF;
;                         *(f32x4*)pp = z0; *(f32x4*)(pp + 4) = z1;
;                     } else {
;                         bf16_t* mp = MG + (size_t)(u.pm * BM + rl) * D + colm + bj * HALF;
;                         if (b != 0) { const u32x4 pv = *(const u32x4*)mp;
;                             z0 += (f32x4){lo16(pv.x), hi16(pv.x), lo16(pv.y), hi16(pv.y)}; z1 += (f32x4){lo16(pv.z), hi16(pv.z), lo16(pv.w), hi16(pv.w)}; }
;                         u32x4 w; w.x = pk2(z0[0], z0[1]); w.y = pk2(z0[2], z0[3]); w.z = pk2(z1[0], z1[1]); w.w = pk2(z1[2], z1[3]);
;                         *(u32x4*)mp = w;
.LBB0_256:
	s_nop 0
	v_pk_mul_f32 v[40:41], v[40:41], s[96:97] op_sel_hi:[1,0]
	v_pk_mul_f32 v[38:39], v[38:39], s[96:97] op_sel_hi:[1,0]
	v_pk_mul_f32 v[44:45], v[36:37], s[96:97] op_sel_hi:[1,0]
	v_pk_mul_f32 v[46:47], v[34:35], s[96:97] op_sel_hi:[1,0]
	s_mov_b64 s[58:59], -1
	s_and_b64 vcc, exec, s[46:47]
	s_nop 0
	v_cvt_f32_ubyte1_e32 v35, v240
	v_cvt_f32_ubyte0_e32 v34, v240
	v_cvt_f32_ubyte3_e32 v37, v240
	v_cvt_f32_ubyte2_e32 v36, v240
	v_pk_mul_f32 v[36:37], v[40:41], v[36:37]
	v_pk_mul_f32 v[34:35], v[38:39], v[34:35]
	v_cvt_f32_ubyte1_e32 v39, v241
	v_cvt_f32_ubyte0_e32 v38, v241
	v_cvt_f32_ubyte3_e32 v41, v241
	v_cvt_f32_ubyte2_e32 v40, v241
	v_pk_mul_f32 v[40:41], v[44:45], v[40:41]
	v_pk_mul_f32 v[38:39], v[46:47], v[38:39]
	s_cbranch_vccnz .LBB0_260
	v_mov_b64_e32 v[48:49], v[40:41]
	v_mov_b64_e32 v[44:45], v[36:37]
	v_lshl_add_u64 v[52:53], v[60:61], 0, v[0:1]
	s_and_b64 vcc, exec, s[4:5]
	v_mov_b64_e32 v[46:47], v[38:39]
	v_mov_b64_e32 v[42:43], v[34:35]
	s_cbranch_vccnz .LBB0_259
	global_load_dwordx4 v[42:45], v[52:53], off offset:256
	s_waitcnt vmcnt(0)
	v_lshlrev_b32_e32 v46, 16, v42
	v_and_b32_e32 v47, 0xffff0000, v42
	v_lshlrev_b32_e32 v42, 16, v43
	v_and_b32_e32 v43, 0xffff0000, v43
	v_lshlrev_b32_e32 v54, 16, v44
	v_and_b32_e32 v55, 0xffff0000, v44
	v_lshlrev_b32_e32 v48, 16, v45
	v_and_b32_e32 v49, 0xffff0000, v45
	v_pk_add_f32 v[44:45], v[36:37], v[42:43]
	v_pk_add_f32 v[42:43], v[34:35], v[46:47]
	v_pk_add_f32 v[48:49], v[40:41], v[48:49]
	v_pk_add_f32 v[46:47], v[38:39], v[54:55]

; __device__ __forceinline__ unsigned pk2(float lo, float hi) { const f32x2_t v = {lo, hi}; const bf16x2_t b = __builtin_convertvector(v, bf16x2_t); return __builtin_bit_cast(unsigned, b); }
; __device__ __forceinline__ float lo16(unsigned w) { return __uint_as_float(w << 16); }
; __device__ __forceinline__ float hi16(unsigned w) { return __uint_as_float(w & 0xffff0000u); }
;     __device__ __forceinline__ void operator()(const f32x4 (&acc)[2][2][4][2], const Unit& u, int wr, int wc, int fr, int fq) const {
;     ...
;                 const int rl = rloc + ai * HALF + m * 16;
;                 const unsigned char* gp_ = (const unsigned char*)(Gp + (size_t)(u.pm * BM + rl) * ldg) + colg;
; #pragma unroll
;                 for (int bj = 0; bj < 2; ++bj) {
;                     const u32x2 gp = *(const u32x2*)(gp_ + bj * HALF);
;                     const f32x4 v0 = acc[ai][bj][m][0] * (1.0f / 255.0f), v1 = acc[ai][bj][m][1] * (1.0f / 255.0f);
;                     f32x4 z0 = {(float)(gp.x & 255u) * v0[0], (float)((gp.x >> 8) & 255u) * v0[1], (float)((gp.x >> 16) & 255u) * v0[2], (float)(gp.x >> 24) * v0[3]};
;                     f32x4 z1 = {(float)(gp.y & 255u) * v1[0], (float)((gp.y >> 8) & 255u) * v1[1], (float)((gp.y >> 16) & 255u) * v1[2], (float)(gp.y >> 24) * v1[3]};
;                     if (ctx) {
;                         float* pp = part + ((size_t)(b * 256 + rl)) * D + colm + bj * HALF;
;                         *(f32x4*)pp = z0; *(f32x4*)(pp + 4) = z1;
;                     } else {
;                         bf16_t* mp = MG + (size_t)(u.pm * BM + rl) * D + colm + bj * HALF;
;                         if (b != 0) { const u32x4 pv = *(const u32x4*)mp;
;                             z0 += (f32x4){lo16(pv.x), hi16(pv.x), lo16(pv.y), hi16(pv.y)}; z1 += (f32x4){lo16(pv.z), hi16(pv.z), lo16(pv.w), hi16(pv.w)}; }
;                         u32x4 w; w.x = pk2(z0[0], z0[1]); w.y = pk2(z0[2], z0[3]); w.z = pk2(z1[0], z1[1]); w.w = pk2(z1[2], z1[3]);
;                         *(u32x4*)mp = w;
.LBB0_262:
	s_nop 0
	v_add_u32_e32 v34, s7, v173
	v_mov_b64_e32 v[36:37], s[90:91]
	v_mad_i64_i32 v[36:37], s[22:23], v34, s21, v[36:37]
	v_lshl_add_u64 v[42:43], v[36:37], 0, v[146:147]
	s_nop 0
	v_ashrrev_i32_e32 v35, 31, v34
	v_pk_mul_f32 v[32:33], v[32:33], s[96:97] op_sel_hi:[1,0]
	v_pk_mul_f32 v[30:31], v[30:31], s[96:97] op_sel_hi:[1,0]
	v_pk_mul_f32 v[38:39], v[28:29], s[96:97] op_sel_hi:[1,0]
	v_pk_mul_f32 v[40:41], v[26:27], s[96:97] op_sel_hi:[1,0]
	v_lshlrev_b64 v[34:35], 11, v[34:35]
	s_mov_b64 s[58:59], -1
	s_and_b64 vcc, exec, s[46:47]
	v_lshl_add_u64 v[44:45], s[84:85], 0, v[34:35]
	s_nop 0
	v_cvt_f32_ubyte1_e32 v27, v194
	v_cvt_f32_ubyte0_e32 v26, v194
	v_cvt_f32_ubyte3_e32 v29, v194
	v_cvt_f32_ubyte2_e32 v28, v194
	v_pk_mul_f32 v[28:29], v[32:33], v[28:29]
	v_pk_mul_f32 v[26:27], v[30:31], v[26:27]
	v_cvt_f32_ubyte1_e32 v31, v195
	v_cvt_f32_ubyte0_e32 v30, v195
	v_cvt_f32_ubyte3_e32 v33, v195
	v_cvt_f32_ubyte2_e32 v32, v195
	v_pk_mul_f32 v[32:33], v[38:39], v[32:33]
	v_pk_mul_f32 v[30:31], v[40:41], v[30:31]
	s_cbranch_vccnz .LBB0_266
	v_mov_b64_e32 v[40:41], v[32:33]
	v_mov_b64_e32 v[36:37], v[28:29]
	v_lshl_add_u64 v[46:47], v[44:45], 0, v[0:1]
	s_and_b64 vcc, exec, s[4:5]
	v_mov_b64_e32 v[38:39], v[30:31]
	v_mov_b64_e32 v[34:35], v[26:27]
	s_cbranch_vccnz .LBB0_265
	global_load_dwordx4 v[34:37], v[46:47], off
	s_waitcnt vmcnt(0)
	v_lshlrev_b32_e32 v38, 16, v34
	v_and_b32_e32 v39, 0xffff0000, v34
	v_lshlrev_b32_e32 v34, 16, v35
	v_and_b32_e32 v35, 0xffff0000, v35
	v_lshlrev_b32_e32 v48, 16, v36
	v_and_b32_e32 v49, 0xffff0000, v36
	v_lshlrev_b32_e32 v40, 16, v37
	v_and_b32_e32 v41, 0xffff0000, v37
	v_pk_add_f32 v[36:37], v[28:29], v[34:35]
	v_pk_add_f32 v[34:35], v[26:27], v[38:39]
	v_pk_add_f32 v[40:41], v[32:33], v[40:41]
	v_pk_add_f32 v[38:39], v[30:31], v[48:49]

; __device__ __forceinline__ unsigned pk2(float lo, float hi) { const f32x2_t v = {lo, hi}; const bf16x2_t b = __builtin_convertvector(v, bf16x2_t); return __builtin_bit_cast(unsigned, b); }
; __device__ __forceinline__ float lo16(unsigned w) { return __uint_as_float(w << 16); }
; __device__ __forceinline__ float hi16(unsigned w) { return __uint_as_float(w & 0xffff0000u); }
;     __device__ __forceinline__ void operator()(const f32x4 (&acc)[2][2][4][2], const Unit& u, int wr, int wc, int fr, int fq) const {
;     ...
;                     const u32x2 gp = *(const u32x2*)(gp_ + bj * HALF);
;                     const f32x4 v0 = acc[ai][bj][m][0] * (1.0f / 255.0f), v1 = acc[ai][bj][m][1] * (1.0f / 255.0f);
;                     f32x4 z0 = {(float)(gp.x & 255u) * v0[0], (float)((gp.x >> 8) & 255u) * v0[1], (float)((gp.x >> 16) & 255u) * v0[2], (float)(gp.x >> 24) * v0[3]};
;                     f32x4 z1 = {(float)(gp.y & 255u) * v1[0], (float)((gp.y >> 8) & 255u) * v1[1], (float)((gp.y >> 16) & 255u) * v1[2], (float)(gp.y >> 24) * v1[3]};
;                     if (ctx) {
;                         float* pp = part + ((size_t)(b * 256 + rl)) * D + colm + bj * HALF;
;                         *(f32x4*)pp = z0; *(f32x4*)(pp + 4) = z1;
;                     } else {
;                         bf16_t* mp = MG + (size_t)(u.pm * BM + rl) * D + colm + bj * HALF;
;                         if (b != 0) { const u32x4 pv = *(const u32x4*)mp;
;                             z0 += (f32x4){lo16(pv.x), hi16(pv.x), lo16(pv.y), hi16(pv.y)}; z1 += (f32x4){lo16(pv.z), hi16(pv.z), lo16(pv.w), hi16(pv.w)}; }
;                         u32x4 w; w.x = pk2(z0[0], z0[1]); w.y = pk2(z0[2], z0[3]); w.z = pk2(z1[0], z1[1]); w.w = pk2(z1[2], z1[3]);
;                         *(u32x4*)mp = w;
.LBB0_268:
	s_nop 0
	v_pk_mul_f32 v[24:25], v[24:25], s[96:97] op_sel_hi:[1,0]
	v_pk_mul_f32 v[22:23], v[22:23], s[96:97] op_sel_hi:[1,0]
	v_pk_mul_f32 v[28:29], v[20:21], s[96:97] op_sel_hi:[1,0]
	v_pk_mul_f32 v[30:31], v[18:19], s[96:97] op_sel_hi:[1,0]
	s_mov_b64 s[58:59], -1
	s_and_b64 vcc, exec, s[46:47]
	s_nop 0
	v_cvt_f32_ubyte1_e32 v19, v196
	v_cvt_f32_ubyte0_e32 v18, v196
	v_cvt_f32_ubyte3_e32 v21, v196
	v_cvt_f32_ubyte2_e32 v20, v196
	v_pk_mul_f32 v[20:21], v[24:25], v[20:21]
	v_pk_mul_f32 v[18:19], v[22:23], v[18:19]
	v_cvt_f32_ubyte1_e32 v23, v197
	v_cvt_f32_ubyte0_e32 v22, v197
	v_cvt_f32_ubyte3_e32 v25, v197
	v_cvt_f32_ubyte2_e32 v24, v197
	v_pk_mul_f32 v[24:25], v[28:29], v[24:25]
	v_pk_mul_f32 v[22:23], v[30:31], v[22:23]
	s_cbranch_vccnz .LBB0_272
	v_mov_b64_e32 v[32:33], v[24:25]
	v_mov_b64_e32 v[28:29], v[20:21]
	v_lshl_add_u64 v[36:37], v[44:45], 0, v[0:1]
	s_and_b64 vcc, exec, s[4:5]
	v_mov_b64_e32 v[30:31], v[22:23]
	v_mov_b64_e32 v[26:27], v[18:19]
	s_cbranch_vccnz .LBB0_271
	global_load_dwordx4 v[26:29], v[36:37], off offset:256
	s_waitcnt vmcnt(0)
	v_lshlrev_b32_e32 v30, 16, v26
	v_and_b32_e32 v31, 0xffff0000, v26
	v_lshlrev_b32_e32 v26, 16, v27
	v_and_b32_e32 v27, 0xffff0000, v27
	v_lshlrev_b32_e32 v38, 16, v28
	v_and_b32_e32 v39, 0xffff0000, v28
	v_lshlrev_b32_e32 v32, 16, v29
	v_and_b32_e32 v33, 0xffff0000, v29
	v_pk_add_f32 v[28:29], v[20:21], v[26:27]
	v_pk_add_f32 v[26:27], v[18:19], v[30:31]
	v_pk_add_f32 v[32:33], v[24:25], v[32:33]
	v_pk_add_f32 v[30:31], v[22:23], v[38:39]

; __device__ __forceinline__ unsigned pk2(float lo, float hi) { const f32x2_t v = {lo, hi}; const bf16x2_t b = __builtin_convertvector(v, bf16x2_t); return __builtin_bit_cast(unsigned, b); }
; __device__ __forceinline__ float lo16(unsigned w) { return __uint_as_float(w << 16); }
; __device__ __forceinline__ float hi16(unsigned w) { return __uint_as_float(w & 0xffff0000u); }
;     __device__ __forceinline__ void operator()(const f32x4 (&acc)[2][2][4][2], const Unit& u, int wr, int wc, int fr, int fq) const {
;     ...
;                 const int rl = rloc + ai * HALF + m * 16;
;                 const unsigned char* gp_ = (const unsigned char*)(Gp + (size_t)(u.pm * BM + rl) * ldg) + colg;
; #pragma unroll
;                 for (int bj = 0; bj < 2; ++bj) {
;                     const u32x2 gp = *(const u32x2*)(gp_ + bj * HALF);
;                     const f32x4 v0 = acc[ai][bj][m][0] * (1.0f / 255.0f), v1 = acc[ai][bj][m][1] * (1.0f / 255.0f);
;                     f32x4 z0 = {(float)(gp.x & 255u) * v0[0], (float)((gp.x >> 8) & 255u) * v0[1], (float)((gp.x >> 16) & 255u) * v0[2], (float)(gp.x >> 24) * v0[3]};
;                     f32x4 z1 = {(float)(gp.y & 255u) * v1[0], (float)((gp.y >> 8) & 255u) * v1[1], (float)((gp.y >> 16) & 255u) * v1[2], (float)(gp.y >> 24) * v1[3]};
;                     if (ctx) {
;                         float* pp = part + ((size_t)(b * 256 + rl)) * D + colm + bj * HALF;
;                         *(f32x4*)pp = z0; *(f32x4*)(pp + 4) = z1;
;                     } else {
;                         bf16_t* mp = MG + (size_t)(u.pm * BM + rl) * D + colm + bj * HALF;
;                         if (b != 0) { const u32x4 pv = *(const u32x4*)mp;
;                             z0 += (f32x4){lo16(pv.x), hi16(pv.x), lo16(pv.y), hi16(pv.y)}; z1 += (f32x4){lo16(pv.z), hi16(pv.z), lo16(pv.w), hi16(pv.w)}; }
;                         u32x4 w; w.x = pk2(z0[0], z0[1]); w.y = pk2(z0[2], z0[3]); w.z = pk2(z1[0], z1[1]); w.w = pk2(z1[2], z1[3]);
;                         *(u32x4*)mp = w;
.LBB0_274:
	s_nop 0
	v_add_u32_e32 v18, s7, v174
	v_mov_b64_e32 v[20:21], s[90:91]
	v_mad_i64_i32 v[20:21], s[22:23], v18, s21, v[20:21]
	v_lshl_add_u64 v[26:27], v[20:21], 0, v[146:147]
	s_nop 0
	v_ashrrev_i32_e32 v19, 31, v18
	v_pk_mul_f32 v[16:17], v[16:17], s[96:97] op_sel_hi:[1,0]
	v_pk_mul_f32 v[14:15], v[14:15], s[96:97] op_sel_hi:[1,0]
	v_pk_mul_f32 v[22:23], v[12:13], s[96:97] op_sel_hi:[1,0]
	v_pk_mul_f32 v[24:25], v[10:11], s[96:97] op_sel_hi:[1,0]
	v_lshlrev_b64 v[18:19], 11, v[18:19]
	s_mov_b64 s[58:59], -1
	s_and_b64 vcc, exec, s[46:47]
	v_lshl_add_u64 v[28:29], s[84:85], 0, v[18:19]
	s_nop 0
	v_cvt_f32_ubyte1_e32 v11, v198
	v_cvt_f32_ubyte0_e32 v10, v198
	v_cvt_f32_ubyte3_e32 v13, v198
	v_cvt_f32_ubyte2_e32 v12, v198
	v_pk_mul_f32 v[12:13], v[16:17], v[12:13]
	v_pk_mul_f32 v[10:11], v[14:15], v[10:11]
	v_cvt_f32_ubyte1_e32 v15, v199
	v_cvt_f32_ubyte0_e32 v14, v199
	v_cvt_f32_ubyte3_e32 v17, v199
	v_cvt_f32_ubyte2_e32 v16, v199
	v_pk_mul_f32 v[16:17], v[22:23], v[16:17]
	v_pk_mul_f32 v[14:15], v[24:25], v[14:15]
	s_cbranch_vccnz .LBB0_278
	v_mov_b64_e32 v[24:25], v[16:17]
	v_mov_b64_e32 v[20:21], v[12:13]
	v_lshl_add_u64 v[30:31], v[28:29], 0, v[0:1]
	s_and_b64 vcc, exec, s[4:5]
	v_mov_b64_e32 v[22:23], v[14:15]
	v_mov_b64_e32 v[18:19], v[10:11]
	s_cbranch_vccnz .LBB0_277
	global_load_dwordx4 v[18:21], v[30:31], off
	s_waitcnt vmcnt(0)
	v_lshlrev_b32_e32 v22, 16, v18
	v_and_b32_e32 v23, 0xffff0000, v18
	v_lshlrev_b32_e32 v18, 16, v19
	v_and_b32_e32 v19, 0xffff0000, v19
	v_lshlrev_b32_e32 v32, 16, v20
	v_and_b32_e32 v33, 0xffff0000, v20
	v_lshlrev_b32_e32 v24, 16, v21
	v_and_b32_e32 v25, 0xffff0000, v21
	v_pk_add_f32 v[20:21], v[12:13], v[18:19]
	v_pk_add_f32 v[18:19], v[10:11], v[22:23]
	v_pk_add_f32 v[24:25], v[16:17], v[24:25]
	v_pk_add_f32 v[22:23], v[14:15], v[32:33]

; __device__ __forceinline__ unsigned pk2(float lo, float hi) { const f32x2_t v = {lo, hi}; const bf16x2_t b = __builtin_convertvector(v, bf16x2_t); return __builtin_bit_cast(unsigned, b); }
; __device__ __forceinline__ float lo16(unsigned w) { return __uint_as_float(w << 16); }
; __device__ __forceinline__ float hi16(unsigned w) { return __uint_as_float(w & 0xffff0000u); }
;     __device__ __forceinline__ void operator()(const f32x4 (&acc)[2][2][4][2], const Unit& u, int wr, int wc, int fr, int fq) const {
;     ...
;                     const u32x2 gp = *(const u32x2*)(gp_ + bj * HALF);
;                     const f32x4 v0 = acc[ai][bj][m][0] * (1.0f / 255.0f), v1 = acc[ai][bj][m][1] * (1.0f / 255.0f);
;                     f32x4 z0 = {(float)(gp.x & 255u) * v0[0], (float)((gp.x >> 8) & 255u) * v0[1], (float)((gp.x >> 16) & 255u) * v0[2], (float)(gp.x >> 24) * v0[3]};
;                     f32x4 z1 = {(float)(gp.y & 255u) * v1[0], (float)((gp.y >> 8) & 255u) * v1[1], (float)((gp.y >> 16) & 255u) * v1[2], (float)(gp.y >> 24) * v1[3]};
;                     if (ctx) {
;                         float* pp = part + ((size_t)(b * 256 + rl)) * D + colm + bj * HALF;
;                         *(f32x4*)pp = z0; *(f32x4*)(pp + 4) = z1;
;                     } else {
;                         bf16_t* mp = MG + (size_t)(u.pm * BM + rl) * D + colm + bj * HALF;
;                         if (b != 0) { const u32x4 pv = *(const u32x4*)mp;
;                             z0 += (f32x4){lo16(pv.x), hi16(pv.x), lo16(pv.y), hi16(pv.y)}; z1 += (f32x4){lo16(pv.z), hi16(pv.z), lo16(pv.w), hi16(pv.w)}; }
;                         u32x4 w; w.x = pk2(z0[0], z0[1]); w.y = pk2(z0[2], z0[3]); w.z = pk2(z1[0], z1[1]); w.w = pk2(z1[2], z1[3]);
;                         *(u32x4*)mp = w;
.LBB0_280:
	s_nop 0
	v_pk_mul_f32 v[8:9], v[8:9], s[96:97] op_sel_hi:[1,0]
	v_pk_mul_f32 v[6:7], v[6:7], s[96:97] op_sel_hi:[1,0]
	v_pk_mul_f32 v[12:13], v[4:5], s[96:97] op_sel_hi:[1,0]
	v_pk_mul_f32 v[14:15], v[2:3], s[96:97] op_sel_hi:[1,0]
	s_and_b64 vcc, exec, s[46:47]
	s_mov_b64 s[46:47], -1
	s_nop 0
	v_cvt_f32_ubyte1_e32 v3, v200
	v_cvt_f32_ubyte0_e32 v2, v200
	v_cvt_f32_ubyte3_e32 v5, v200
	v_cvt_f32_ubyte2_e32 v4, v200
	v_cvt_f32_ubyte1_e32 v17, v201
	v_cvt_f32_ubyte0_e32 v16, v201
	v_cvt_f32_ubyte3_e32 v21, v201
	v_cvt_f32_ubyte2_e32 v20, v201
	v_pk_mul_f32 v[4:5], v[8:9], v[4:5]
	v_pk_mul_f32 v[2:3], v[6:7], v[2:3]
	v_pk_mul_f32 v[8:9], v[12:13], v[20:21]
	v_pk_mul_f32 v[6:7], v[14:15], v[16:17]
	s_cbranch_vccnz .LBB0_284
	v_mov_b64_e32 v[16:17], v[8:9]
	v_mov_b64_e32 v[12:13], v[4:5]
	v_lshl_add_u64 v[20:21], v[28:29], 0, v[0:1]
	s_and_b64 vcc, exec, s[4:5]
	v_mov_b64_e32 v[14:15], v[6:7]
	v_mov_b64_e32 v[10:11], v[2:3]
	s_cbranch_vccnz .LBB0_283
	global_load_dwordx4 v[10:13], v[20:21], off offset:256
	s_waitcnt vmcnt(0)
	v_lshlrev_b32_e32 v14, 16, v10
	v_and_b32_e32 v15, 0xffff0000, v10
	v_lshlrev_b32_e32 v10, 16, v11
	v_and_b32_e32 v11, 0xffff0000, v11
	v_lshlrev_b32_e32 v22, 16, v12
	v_and_b32_e32 v23, 0xffff0000, v12
	v_lshlrev_b32_e32 v16, 16, v13
	v_and_b32_e32 v17, 0xffff0000, v13
	v_pk_add_f32 v[12:13], v[4:5], v[10:11]
	v_pk_add_f32 v[10:11], v[2:3], v[14:15]
	v_pk_add_f32 v[16:17], v[8:9], v[16:17]
	v_pk_add_f32 v[14:15], v[6:7], v[22:23]

; __device__ __forceinline__ void xcd_barrier(const XcdBarrier& b) {
;     asm volatile("s_waitcnt vmcnt(0)" ::: "memory");
;     __syncthreads();
;     if (threadIdx.x == 0) {
;         unsigned* bar = b.bar;
;         __builtin_amdgcn_s_waitcnt(0);
;         unsigned nloc = b.st[0], nx = b.st[1];
;         if (nloc == 0u) { xcd_barrier_complete(bar, b.x, nloc, nx); b.st[0] = nloc; b.st[1] = nx; }
; __global__ void __launch_bounds__(512, 2) mk_fwd(Args args) {
;     ...
;         if (ph + 1 < args.ph_hi) { if (ph == 0) grid.sync(); else xcd_barrier(xbar); if (PROBE_DBL & 128) xcd_barrier(xbar); }
.LBB0_724:
	s_waitcnt vmcnt(0)
	s_waitcnt vmcnt(0)
	s_barrier
	s_mov_b64 s[4:5], exec
	v_readlane_b32 s2, v251, 5
	v_readlane_b32 s3, v251, 6
	s_and_b64 s[2:3], s[4:5], s[2:3]
	s_mov_b64 exec, s[2:3]
	s_cbranch_execz .LBB0_777
	v_readlane_b32 s2, v252, 21
	s_waitcnt vmcnt(0) expcnt(0) lgkmcnt(0)
	s_nop 0
	v_mov_b32_e32 v0, s2
	ds_read_b32 v3, v0
	v_readlane_b32 s2, v252, 22
	s_waitcnt lgkmcnt(0)
	v_cmp_ne_u32_e32 vcc, 0, v3
	v_mov_b32_e32 v0, s2
	ds_read_b32 v2, v0
	s_cbranch_vccnz .LBB0_741
	s_mov_b32 s2, 1
	s_branch .LBB0_729
